# GLA prep phase: fewer VALU per token (1/16 folded into the gate weights, one fma for the ln2 scaling, exponent argument formed once for k_inv and q_dec)
# speedup vs baseline: 1.0035x; 1.0035x over previous
.LBB0_777:
	s_cmp_lt_i32 s90, 8
	s_cselect_b64 s[2:3], -1, 0
	s_add_u32 s36, s88, 0x115d000
	s_addc_u32 s37, s89, 0
	s_and_b64 s[18:19], s[2:3], s[0:1]
	s_andn2_b64 vcc, exec, s[18:19]
	s_cbranch_vccnz .LBB0_852
	s_cmpk_gt_i32 s58, 0x47f
	s_cbranch_scc1 .LBB0_851
	s_waitcnt vmcnt(0)
	v_readfirstlane_b32 s32, v0
	v_and_b32_e32 v2, 63, v0
	s_mov_b32 s33, 0xbfb8aa3b
	s_mov_b32 s35, 0x3f317217
	s_mov_b32 s36, 0xc1b8aa3b
	s_mov_b32 s37, 0xbd317217
	s_lshr_b32 s32, s32, 6
	v_lshlrev_b32_e32 v3, 3, v2
	v_lshlrev_b32_e32 v8, 1, v3
	v_lshlrev_b32_e32 v2, 2, v2
	s_lshl_b32 s92, s32, 10
	s_add_i32 s92, s92, 0x8000
	v_mov_b32_e32 v78, s92
	v_add_u32_e32 v9, s92, v8
	s_lshr_b32 s56, s58, 2
	s_mul_hi_u32 s57, s56, 0x71c71c8
	s_mul_i32 s34, s57, 108
	s_add_i32 s34, s34, s56
	s_and_b32 s57, s58, 3
	s_mul_i32 s57, s57, 36
	s_add_i32 s34, s34, s57
	s_mov_b32 s50, 0
	s_mul_hi_u32 s38, s34, 0x1c71c72
	s_mul_i32 s92, s38, 144
	s_sub_i32 s92, s34, s92
	s_mul_hi_u32 s40, s92, 0x71c71c8
	s_mul_i32 s93, s40, 36
	s_sub_i32 s39, s92, s93
	s_lshl_b32 s92, s38, 8
	s_lshl_b32 s93, s39, 6
	s_add_i32 s92, s92, s93
	s_addk_i32 s92, 0x4000
	s_lshl_b32 s94, s38, 11
	s_add_i32 s94, s94, s93
	s_addk_i32 s94, 0xff00
	s_cmp_lt_u32 s39, 4
	s_cselect_b32 s41, s92, s94
	s_lshl_b32 s92, s32, 3
	s_add_i32 s41, s41, s92
	s_lshl_b32 s95, s40, 8
	s_mul_i32 s92, s41, 0x1800
	s_add_u32 s92, s92, s95
	s_add_u32 s42, s96, s92
	s_addc_u32 s43, s97, 0
	s_lshl_b32 s92, s41, 10
	s_add_u32 s92, s92, s95
	s_add_u32 s44, s88, 0xa27d000
	s_addc_u32 s45, s89, 0
	s_add_u32 s44, s44, s92
	s_addc_u32 s45, s45, 0
	s_add_u32 s46, s44, 0x1000000
	s_addc_u32 s47, s45, 0
	s_lshl_b32 s92, s41, 7
	s_add_u32 s48, s88, 0xf1d000
	s_addc_u32 s49, s89, 0
	s_add_u32 s48, s48, s92
	s_addc_u32 s49, s49, 0
	s_lshl_b32 s95, s40, 9
	v_readlane_b32 s52, v251, 18
	v_readlane_b32 s53, v251, 19
	s_nop 3
	s_add_u32 s52, s52, s95
	s_addc_u32 s53, s53, 0
	global_load_dwordx2 v[10:11], v3, s[52:53]
	global_load_dwordx2 v[12:13], v3, s[52:53] offset:2048
	s_add_u32 s52, s52, 0x1000
	s_addc_u32 s53, s53, 0
	global_load_dwordx2 v[14:15], v3, s[52:53]
	global_load_dwordx2 v[16:17], v3, s[52:53] offset:2048
	s_add_u32 s52, s52, 0x1000
	s_addc_u32 s53, s53, 0
	global_load_dwordx2 v[18:19], v3, s[52:53]
	global_load_dwordx2 v[20:21], v3, s[52:53] offset:2048
	s_add_u32 s52, s52, 0x1000
	s_addc_u32 s53, s53, 0
	global_load_dwordx2 v[22:23], v3, s[52:53]
	global_load_dwordx2 v[24:25], v3, s[52:53] offset:2048
	s_add_u32 s52, s52, 0x1000
	s_addc_u32 s53, s53, 0
	global_load_dwordx2 v[26:27], v3, s[52:53]
	global_load_dwordx2 v[28:29], v3, s[52:53] offset:2048
	s_add_u32 s52, s52, 0x1000
	s_addc_u32 s53, s53, 0
	global_load_dwordx2 v[30:31], v3, s[52:53]
	global_load_dwordx2 v[32:33], v3, s[52:53] offset:2048
	s_add_u32 s52, s52, 0x1000
	s_addc_u32 s53, s53, 0
	global_load_dwordx2 v[34:35], v3, s[52:53]
	global_load_dwordx2 v[36:37], v3, s[52:53] offset:2048
	s_add_u32 s52, s52, 0x1000
	s_addc_u32 s53, s53, 0
	global_load_dwordx2 v[38:39], v3, s[52:53]
	global_load_dwordx2 v[40:41], v3, s[52:53] offset:2048
	v_readlane_b32 s52, v251, 24
	v_readlane_b32 s53, v251, 25
	s_nop 3
	s_add_u32 s52, s52, s95
	s_addc_u32 s53, s53, 0
	global_load_dwordx2 v[42:43], v3, s[52:53]
	global_load_dwordx2 v[44:45], v3, s[52:53] offset:2048
	s_add_u32 s52, s52, 0x1000
	s_addc_u32 s53, s53, 0
	global_load_dwordx2 v[46:47], v3, s[52:53]
	global_load_dwordx2 v[48:49], v3, s[52:53] offset:2048
	s_add_u32 s52, s52, 0x1000
	s_addc_u32 s53, s53, 0
	global_load_dwordx2 v[50:51], v3, s[52:53]
	global_load_dwordx2 v[52:53], v3, s[52:53] offset:2048
	s_add_u32 s52, s52, 0x1000
	s_addc_u32 s53, s53, 0
	global_load_dwordx2 v[54:55], v3, s[52:53]
	global_load_dwordx2 v[56:57], v3, s[52:53] offset:2048
	s_add_u32 s52, s52, 0x1000
	s_addc_u32 s53, s53, 0
	global_load_dwordx2 v[58:59], v3, s[52:53]
	global_load_dwordx2 v[60:61], v3, s[52:53] offset:2048
	s_add_u32 s52, s52, 0x1000
	s_addc_u32 s53, s53, 0
	global_load_dwordx2 v[62:63], v3, s[52:53]
	global_load_dwordx2 v[64:65], v3, s[52:53] offset:2048
	s_add_u32 s52, s52, 0x1000
	s_addc_u32 s53, s53, 0
	global_load_dwordx2 v[66:67], v3, s[52:53]
	global_load_dwordx2 v[68:69], v3, s[52:53] offset:2048
	s_add_u32 s52, s52, 0x1000
	s_addc_u32 s53, s53, 0
	global_load_dwordx2 v[70:71], v3, s[52:53]
	global_load_dwordx2 v[72:73], v3, s[52:53] offset:2048
	v_readlane_b32 s52, v251, 20
	v_readlane_b32 s53, v251, 21
	s_nop 3
	s_add_u32 s52, s52, s95
	s_addc_u32 s53, s53, 0
	global_load_dwordx2 v[74:75], v3, s[52:53]
	v_readlane_b32 s52, v251, 26
	v_readlane_b32 s53, v251, 27
	s_nop 3
	s_add_u32 s52, s52, s95
	s_addc_u32 s53, s53, 0
	global_load_dwordx2 v[76:77], v3, s[52:53]
	global_load_dwordx4 v[4:7], v8, s[48:49]
	s_mov_b64 s[52:53], s[42:43]
	global_load_dword v200, v2, s[52:53] offset:1024
	s_add_u32 s52, s52, 0x1800
	s_addc_u32 s53, s53, 0
	global_load_dword v201, v2, s[52:53] offset:1024
	s_add_u32 s52, s52, 0x1800
	s_addc_u32 s53, s53, 0
	global_load_dword v202, v2, s[52:53] offset:1024
	s_add_u32 s52, s52, 0x1800
	s_addc_u32 s53, s53, 0
	global_load_dword v203, v2, s[52:53] offset:1024
	s_add_u32 s52, s52, 0x1800
	s_addc_u32 s53, s53, 0
	global_load_dword v204, v2, s[52:53] offset:1024
	s_add_u32 s52, s52, 0x1800
	s_addc_u32 s53, s53, 0
	global_load_dword v205, v2, s[52:53] offset:1024
	s_add_u32 s52, s52, 0x1800
	s_addc_u32 s53, s53, 0
	global_load_dword v206, v2, s[52:53] offset:1024
	s_add_u32 s52, s52, 0x1800
	s_addc_u32 s53, s53, 0
	global_load_dword v207, v2, s[52:53] offset:1024
	s_cmp_lt_u32 s39, 4
	s_cbranch_scc1 .Lp7_noq_load_first
	s_mov_b64 s[52:53], s[42:43]
	global_load_dword v208, v2, s[52:53]
	s_add_u32 s52, s52, 0x1800
	s_addc_u32 s53, s53, 0
	global_load_dword v209, v2, s[52:53]
	s_add_u32 s52, s52, 0x1800
	s_addc_u32 s53, s53, 0
	global_load_dword v210, v2, s[52:53]
	s_add_u32 s52, s52, 0x1800
	s_addc_u32 s53, s53, 0
	global_load_dword v211, v2, s[52:53]
	s_add_u32 s52, s52, 0x1800
	s_addc_u32 s53, s53, 0
	global_load_dword v212, v2, s[52:53]
	s_add_u32 s52, s52, 0x1800
	s_addc_u32 s53, s53, 0
	global_load_dword v213, v2, s[52:53]
	s_add_u32 s52, s52, 0x1800
	s_addc_u32 s53, s53, 0
	global_load_dword v214, v2, s[52:53]
	s_add_u32 s52, s52, 0x1800
	s_addc_u32 s53, s53, 0
	global_load_dword v215, v2, s[52:53]
.Lp7_noq_load_first:
	s_waitcnt vmcnt(0)
	s_mov_b32 s35, 0x3d800000
	v_pk_mul_f32 v[10:11], v[10:11], s[34:35] op_sel:[0,1] op_sel_hi:[1,1]
	v_pk_mul_f32 v[42:43], v[42:43], s[34:35] op_sel:[0,1] op_sel_hi:[1,1]
	v_pk_mul_f32 v[12:13], v[12:13], s[34:35] op_sel:[0,1] op_sel_hi:[1,1]
	v_pk_mul_f32 v[44:45], v[44:45], s[34:35] op_sel:[0,1] op_sel_hi:[1,1]
	v_pk_mul_f32 v[14:15], v[14:15], s[34:35] op_sel:[0,1] op_sel_hi:[1,1]
	v_pk_mul_f32 v[46:47], v[46:47], s[34:35] op_sel:[0,1] op_sel_hi:[1,1]
	v_pk_mul_f32 v[16:17], v[16:17], s[34:35] op_sel:[0,1] op_sel_hi:[1,1]
	v_pk_mul_f32 v[48:49], v[48:49], s[34:35] op_sel:[0,1] op_sel_hi:[1,1]
	v_pk_mul_f32 v[18:19], v[18:19], s[34:35] op_sel:[0,1] op_sel_hi:[1,1]
	v_pk_mul_f32 v[50:51], v[50:51], s[34:35] op_sel:[0,1] op_sel_hi:[1,1]
	v_pk_mul_f32 v[20:21], v[20:21], s[34:35] op_sel:[0,1] op_sel_hi:[1,1]
	v_pk_mul_f32 v[52:53], v[52:53], s[34:35] op_sel:[0,1] op_sel_hi:[1,1]
	v_pk_mul_f32 v[22:23], v[22:23], s[34:35] op_sel:[0,1] op_sel_hi:[1,1]
	v_pk_mul_f32 v[54:55], v[54:55], s[34:35] op_sel:[0,1] op_sel_hi:[1,1]
	v_pk_mul_f32 v[24:25], v[24:25], s[34:35] op_sel:[0,1] op_sel_hi:[1,1]
	v_pk_mul_f32 v[56:57], v[56:57], s[34:35] op_sel:[0,1] op_sel_hi:[1,1]
	v_pk_mul_f32 v[26:27], v[26:27], s[34:35] op_sel:[0,1] op_sel_hi:[1,1]
	v_pk_mul_f32 v[58:59], v[58:59], s[34:35] op_sel:[0,1] op_sel_hi:[1,1]
	v_pk_mul_f32 v[28:29], v[28:29], s[34:35] op_sel:[0,1] op_sel_hi:[1,1]
	v_pk_mul_f32 v[60:61], v[60:61], s[34:35] op_sel:[0,1] op_sel_hi:[1,1]
	v_pk_mul_f32 v[30:31], v[30:31], s[34:35] op_sel:[0,1] op_sel_hi:[1,1]
	v_pk_mul_f32 v[62:63], v[62:63], s[34:35] op_sel:[0,1] op_sel_hi:[1,1]
	v_pk_mul_f32 v[32:33], v[32:33], s[34:35] op_sel:[0,1] op_sel_hi:[1,1]
	v_pk_mul_f32 v[64:65], v[64:65], s[34:35] op_sel:[0,1] op_sel_hi:[1,1]
	v_pk_mul_f32 v[34:35], v[34:35], s[34:35] op_sel:[0,1] op_sel_hi:[1,1]
	v_pk_mul_f32 v[66:67], v[66:67], s[34:35] op_sel:[0,1] op_sel_hi:[1,1]
	v_pk_mul_f32 v[36:37], v[36:37], s[34:35] op_sel:[0,1] op_sel_hi:[1,1]
	v_pk_mul_f32 v[68:69], v[68:69], s[34:35] op_sel:[0,1] op_sel_hi:[1,1]
	v_pk_mul_f32 v[38:39], v[38:39], s[34:35] op_sel:[0,1] op_sel_hi:[1,1]
	v_pk_mul_f32 v[70:71], v[70:71], s[34:35] op_sel:[0,1] op_sel_hi:[1,1]
	v_pk_mul_f32 v[40:41], v[40:41], s[34:35] op_sel:[0,1] op_sel_hi:[1,1]
	v_pk_mul_f32 v[72:73], v[72:73], s[34:35] op_sel:[0,1] op_sel_hi:[1,1]
	v_pk_mul_f32 v[74:75], v[74:75], s[34:35] op_sel:[0,1] op_sel_hi:[1,1]
	v_pk_mul_f32 v[76:77], v[76:77], s[34:35] op_sel:[0,1] op_sel_hi:[1,1]
.Lp7_item:
	v_mov_b32_e32 v80, v200
	v_mov_b32_e32 v81, v201
	v_mov_b32_e32 v82, v202
	v_mov_b32_e32 v83, v203
	v_mov_b32_e32 v84, v204
	v_mov_b32_e32 v85, v205
	v_mov_b32_e32 v86, v206
	v_mov_b32_e32 v87, v207
	v_mov_b32_e32 v88, v208
	v_mov_b32_e32 v89, v209
	v_mov_b32_e32 v90, v210
	v_mov_b32_e32 v91, v211
	v_mov_b32_e32 v92, v212
	v_mov_b32_e32 v93, v213
	v_mov_b32_e32 v94, v214
	v_mov_b32_e32 v95, v215
	ds_write_b128 v9, v[4:7]
	ds_read_b128 v[216:219], v78 offset:0
	ds_read_b128 v[220:223], v78 offset:16
	ds_read_b128 v[224:227], v78 offset:32
	ds_read_b128 v[228:231], v78 offset:48
	ds_read_b128 v[232:235], v78 offset:64
	ds_read_b128 v[236:239], v78 offset:80
	ds_read_b128 v[240:243], v78 offset:96
	ds_read_b128 v[244:247], v78 offset:112
	s_waitcnt lgkmcnt(0)
	v_pk_fma_f32 v[128:129], v[10:11], v[216:217], v[74:75] op_sel_hi:[1,0,1]
	v_pk_fma_f32 v[128:129], v[12:13], v[216:217], v[128:129] op_sel:[0,1,0] op_sel_hi:[1,1,1]
	v_pk_fma_f32 v[128:129], v[14:15], v[218:219], v[128:129] op_sel_hi:[1,0,1]
	v_pk_fma_f32 v[128:129], v[16:17], v[218:219], v[128:129] op_sel:[0,1,0] op_sel_hi:[1,1,1]
	v_pk_fma_f32 v[128:129], v[18:19], v[220:221], v[128:129] op_sel_hi:[1,0,1]
	v_pk_fma_f32 v[128:129], v[20:21], v[220:221], v[128:129] op_sel:[0,1,0] op_sel_hi:[1,1,1]
	v_pk_fma_f32 v[128:129], v[22:23], v[222:223], v[128:129] op_sel_hi:[1,0,1]
	v_pk_fma_f32 v[128:129], v[24:25], v[222:223], v[128:129] op_sel:[0,1,0] op_sel_hi:[1,1,1]
	v_pk_fma_f32 v[128:129], v[26:27], v[224:225], v[128:129] op_sel_hi:[1,0,1]
	v_pk_fma_f32 v[128:129], v[28:29], v[224:225], v[128:129] op_sel:[0,1,0] op_sel_hi:[1,1,1]
	v_pk_fma_f32 v[128:129], v[30:31], v[226:227], v[128:129] op_sel_hi:[1,0,1]
	v_pk_fma_f32 v[128:129], v[32:33], v[226:227], v[128:129] op_sel:[0,1,0] op_sel_hi:[1,1,1]
	v_pk_fma_f32 v[128:129], v[34:35], v[228:229], v[128:129] op_sel_hi:[1,0,1]
	v_pk_fma_f32 v[128:129], v[36:37], v[228:229], v[128:129] op_sel:[0,1,0] op_sel_hi:[1,1,1]
	v_pk_fma_f32 v[128:129], v[38:39], v[230:231], v[128:129] op_sel_hi:[1,0,1]
	v_pk_fma_f32 v[128:129], v[40:41], v[230:231], v[128:129] op_sel:[0,1,0] op_sel_hi:[1,1,1]
	ds_read_b128 v[216:219], v78 offset:128
	ds_read_b128 v[220:223], v78 offset:144
	ds_read_b128 v[224:227], v78 offset:160
	ds_read_b128 v[228:231], v78 offset:176
	v_pk_fma_f32 v[130:131], v[42:43], v[232:233], v[76:77] op_sel_hi:[1,0,1]
	v_pk_fma_f32 v[130:131], v[44:45], v[232:233], v[130:131] op_sel:[0,1,0] op_sel_hi:[1,1,1]
	v_pk_fma_f32 v[130:131], v[46:47], v[234:235], v[130:131] op_sel_hi:[1,0,1]
	v_pk_fma_f32 v[130:131], v[48:49], v[234:235], v[130:131] op_sel:[0,1,0] op_sel_hi:[1,1,1]
	v_pk_fma_f32 v[130:131], v[50:51], v[236:237], v[130:131] op_sel_hi:[1,0,1]
	v_pk_fma_f32 v[130:131], v[52:53], v[236:237], v[130:131] op_sel:[0,1,0] op_sel_hi:[1,1,1]
	v_pk_fma_f32 v[130:131], v[54:55], v[238:239], v[130:131] op_sel_hi:[1,0,1]
	v_pk_fma_f32 v[130:131], v[56:57], v[238:239], v[130:131] op_sel:[0,1,0] op_sel_hi:[1,1,1]
	v_pk_fma_f32 v[130:131], v[58:59], v[240:241], v[130:131] op_sel_hi:[1,0,1]
	v_pk_fma_f32 v[130:131], v[60:61], v[240:241], v[130:131] op_sel:[0,1,0] op_sel_hi:[1,1,1]
	v_pk_fma_f32 v[130:131], v[62:63], v[242:243], v[130:131] op_sel_hi:[1,0,1]
	v_pk_fma_f32 v[130:131], v[64:65], v[242:243], v[130:131] op_sel:[0,1,0] op_sel_hi:[1,1,1]
	v_pk_fma_f32 v[130:131], v[66:67], v[244:245], v[130:131] op_sel_hi:[1,0,1]
	v_pk_fma_f32 v[130:131], v[68:69], v[244:245], v[130:131] op_sel:[0,1,0] op_sel_hi:[1,1,1]
	v_pk_fma_f32 v[130:131], v[70:71], v[246:247], v[130:131] op_sel_hi:[1,0,1]
	v_pk_fma_f32 v[130:131], v[72:73], v[246:247], v[130:131] op_sel:[0,1,0] op_sel_hi:[1,1,1]
	ds_read_b128 v[232:235], v78 offset:192
	ds_read_b128 v[236:239], v78 offset:208
	ds_read_b128 v[240:243], v78 offset:224
	ds_read_b128 v[244:247], v78 offset:240
	v_pk_mul_f32 v[132:133], v[128:129], s[36:37] op_sel_hi:[1,0]
	v_pk_mul_f32 v[134:135], v[130:131], s[36:37] op_sel_hi:[1,0]
	v_exp_f32_e64 v132, -|v132|
	v_exp_f32_e64 v133, -|v133|
	v_exp_f32_e64 v134, -|v134|
	v_exp_f32_e64 v135, -|v135|
	v_pk_add_f32 v[132:133], v[132:133], 1.0 op_sel_hi:[1,0]
	v_pk_add_f32 v[134:135], v[134:135], 1.0 op_sel_hi:[1,0]
	v_log_f32_e32 v136, v132
	v_log_f32_e32 v137, v133
	v_log_f32_e32 v138, v134
	v_log_f32_e32 v139, v135
	v_min_f32_e32 v128, 0, v128
	v_min_f32_e32 v129, 0, v129
	v_min_f32_e32 v130, 0, v130
	v_min_f32_e32 v131, 0, v131
	v_pk_fma_f32 v[96:97], v[136:137], s[36:37], v[128:129] op_sel:[0,1,0] op_sel_hi:[1,1,1]
	v_pk_fma_f32 v[112:113], v[138:139], s[36:37], v[130:131] op_sel:[0,1,0] op_sel_hi:[1,1,1]
	s_waitcnt lgkmcnt(0)
	v_pk_fma_f32 v[128:129], v[10:11], v[216:217], v[74:75] op_sel_hi:[1,0,1]
	v_pk_fma_f32 v[128:129], v[12:13], v[216:217], v[128:129] op_sel:[0,1,0] op_sel_hi:[1,1,1]
	v_pk_fma_f32 v[128:129], v[14:15], v[218:219], v[128:129] op_sel_hi:[1,0,1]
	v_pk_fma_f32 v[128:129], v[16:17], v[218:219], v[128:129] op_sel:[0,1,0] op_sel_hi:[1,1,1]
	v_pk_fma_f32 v[128:129], v[18:19], v[220:221], v[128:129] op_sel_hi:[1,0,1]
	v_pk_fma_f32 v[128:129], v[20:21], v[220:221], v[128:129] op_sel:[0,1,0] op_sel_hi:[1,1,1]
	v_pk_fma_f32 v[128:129], v[22:23], v[222:223], v[128:129] op_sel_hi:[1,0,1]
	v_pk_fma_f32 v[128:129], v[24:25], v[222:223], v[128:129] op_sel:[0,1,0] op_sel_hi:[1,1,1]
	v_pk_fma_f32 v[128:129], v[26:27], v[224:225], v[128:129] op_sel_hi:[1,0,1]
	v_pk_fma_f32 v[128:129], v[28:29], v[224:225], v[128:129] op_sel:[0,1,0] op_sel_hi:[1,1,1]
	v_pk_fma_f32 v[128:129], v[30:31], v[226:227], v[128:129] op_sel_hi:[1,0,1]
	v_pk_fma_f32 v[128:129], v[32:33], v[226:227], v[128:129] op_sel:[0,1,0] op_sel_hi:[1,1,1]
	v_pk_fma_f32 v[128:129], v[34:35], v[228:229], v[128:129] op_sel_hi:[1,0,1]
	v_pk_fma_f32 v[128:129], v[36:37], v[228:229], v[128:129] op_sel:[0,1,0] op_sel_hi:[1,1,1]
	v_pk_fma_f32 v[128:129], v[38:39], v[230:231], v[128:129] op_sel_hi:[1,0,1]
	v_pk_fma_f32 v[128:129], v[40:41], v[230:231], v[128:129] op_sel:[0,1,0] op_sel_hi:[1,1,1]
	ds_read_b128 v[216:219], v78 offset:256
	ds_read_b128 v[220:223], v78 offset:272
	ds_read_b128 v[224:227], v78 offset:288
	ds_read_b128 v[228:231], v78 offset:304
	v_pk_fma_f32 v[130:131], v[42:43], v[232:233], v[76:77] op_sel_hi:[1,0,1]
	v_pk_fma_f32 v[130:131], v[44:45], v[232:233], v[130:131] op_sel:[0,1,0] op_sel_hi:[1,1,1]
	v_pk_fma_f32 v[130:131], v[46:47], v[234:235], v[130:131] op_sel_hi:[1,0,1]
	v_pk_fma_f32 v[130:131], v[48:49], v[234:235], v[130:131] op_sel:[0,1,0] op_sel_hi:[1,1,1]
	v_pk_fma_f32 v[130:131], v[50:51], v[236:237], v[130:131] op_sel_hi:[1,0,1]
	v_pk_fma_f32 v[130:131], v[52:53], v[236:237], v[130:131] op_sel:[0,1,0] op_sel_hi:[1,1,1]
	v_pk_fma_f32 v[130:131], v[54:55], v[238:239], v[130:131] op_sel_hi:[1,0,1]
	v_pk_fma_f32 v[130:131], v[56:57], v[238:239], v[130:131] op_sel:[0,1,0] op_sel_hi:[1,1,1]
	v_pk_fma_f32 v[130:131], v[58:59], v[240:241], v[130:131] op_sel_hi:[1,0,1]
	v_pk_fma_f32 v[130:131], v[60:61], v[240:241], v[130:131] op_sel:[0,1,0] op_sel_hi:[1,1,1]
	v_pk_fma_f32 v[130:131], v[62:63], v[242:243], v[130:131] op_sel_hi:[1,0,1]
	v_pk_fma_f32 v[130:131], v[64:65], v[242:243], v[130:131] op_sel:[0,1,0] op_sel_hi:[1,1,1]
	v_pk_fma_f32 v[130:131], v[66:67], v[244:245], v[130:131] op_sel_hi:[1,0,1]
	v_pk_fma_f32 v[130:131], v[68:69], v[244:245], v[130:131] op_sel:[0,1,0] op_sel_hi:[1,1,1]
	v_pk_fma_f32 v[130:131], v[70:71], v[246:247], v[130:131] op_sel_hi:[1,0,1]
	v_pk_fma_f32 v[130:131], v[72:73], v[246:247], v[130:131] op_sel:[0,1,0] op_sel_hi:[1,1,1]
	ds_read_b128 v[232:235], v78 offset:320
	ds_read_b128 v[236:239], v78 offset:336
	ds_read_b128 v[240:243], v78 offset:352
	ds_read_b128 v[244:247], v78 offset:368
	v_pk_mul_f32 v[132:133], v[128:129], s[36:37] op_sel_hi:[1,0]
	v_pk_mul_f32 v[134:135], v[130:131], s[36:37] op_sel_hi:[1,0]
	v_exp_f32_e64 v132, -|v132|
	v_exp_f32_e64 v133, -|v133|
	v_exp_f32_e64 v134, -|v134|
	v_exp_f32_e64 v135, -|v135|
	v_pk_add_f32 v[132:133], v[132:133], 1.0 op_sel_hi:[1,0]
	v_pk_add_f32 v[134:135], v[134:135], 1.0 op_sel_hi:[1,0]
	v_log_f32_e32 v136, v132
	v_log_f32_e32 v137, v133
	v_log_f32_e32 v138, v134
	v_log_f32_e32 v139, v135
	v_min_f32_e32 v128, 0, v128
	v_min_f32_e32 v129, 0, v129
	v_min_f32_e32 v130, 0, v130
	v_min_f32_e32 v131, 0, v131
	v_pk_fma_f32 v[98:99], v[136:137], s[36:37], v[128:129] op_sel:[0,1,0] op_sel_hi:[1,1,1]
	v_pk_fma_f32 v[114:115], v[138:139], s[36:37], v[130:131] op_sel:[0,1,0] op_sel_hi:[1,1,1]
	s_waitcnt lgkmcnt(0)
	v_pk_fma_f32 v[128:129], v[10:11], v[216:217], v[74:75] op_sel_hi:[1,0,1]
	v_pk_fma_f32 v[128:129], v[12:13], v[216:217], v[128:129] op_sel:[0,1,0] op_sel_hi:[1,1,1]
	v_pk_fma_f32 v[128:129], v[14:15], v[218:219], v[128:129] op_sel_hi:[1,0,1]
	v_pk_fma_f32 v[128:129], v[16:17], v[218:219], v[128:129] op_sel:[0,1,0] op_sel_hi:[1,1,1]
	v_pk_fma_f32 v[128:129], v[18:19], v[220:221], v[128:129] op_sel_hi:[1,0,1]
	v_pk_fma_f32 v[128:129], v[20:21], v[220:221], v[128:129] op_sel:[0,1,0] op_sel_hi:[1,1,1]
	v_pk_fma_f32 v[128:129], v[22:23], v[222:223], v[128:129] op_sel_hi:[1,0,1]
	v_pk_fma_f32 v[128:129], v[24:25], v[222:223], v[128:129] op_sel:[0,1,0] op_sel_hi:[1,1,1]
	v_pk_fma_f32 v[128:129], v[26:27], v[224:225], v[128:129] op_sel_hi:[1,0,1]
	v_pk_fma_f32 v[128:129], v[28:29], v[224:225], v[128:129] op_sel:[0,1,0] op_sel_hi:[1,1,1]
	v_pk_fma_f32 v[128:129], v[30:31], v[226:227], v[128:129] op_sel_hi:[1,0,1]
	v_pk_fma_f32 v[128:129], v[32:33], v[226:227], v[128:129] op_sel:[0,1,0] op_sel_hi:[1,1,1]
	v_pk_fma_f32 v[128:129], v[34:35], v[228:229], v[128:129] op_sel_hi:[1,0,1]
	v_pk_fma_f32 v[128:129], v[36:37], v[228:229], v[128:129] op_sel:[0,1,0] op_sel_hi:[1,1,1]
	v_pk_fma_f32 v[128:129], v[38:39], v[230:231], v[128:129] op_sel_hi:[1,0,1]
	v_pk_fma_f32 v[128:129], v[40:41], v[230:231], v[128:129] op_sel:[0,1,0] op_sel_hi:[1,1,1]
	ds_read_b128 v[216:219], v78 offset:384
	ds_read_b128 v[220:223], v78 offset:400
	ds_read_b128 v[224:227], v78 offset:416
	ds_read_b128 v[228:231], v78 offset:432
	v_pk_fma_f32 v[130:131], v[42:43], v[232:233], v[76:77] op_sel_hi:[1,0,1]
	v_pk_fma_f32 v[130:131], v[44:45], v[232:233], v[130:131] op_sel:[0,1,0] op_sel_hi:[1,1,1]
	v_pk_fma_f32 v[130:131], v[46:47], v[234:235], v[130:131] op_sel_hi:[1,0,1]
	v_pk_fma_f32 v[130:131], v[48:49], v[234:235], v[130:131] op_sel:[0,1,0] op_sel_hi:[1,1,1]
	v_pk_fma_f32 v[130:131], v[50:51], v[236:237], v[130:131] op_sel_hi:[1,0,1]
	v_pk_fma_f32 v[130:131], v[52:53], v[236:237], v[130:131] op_sel:[0,1,0] op_sel_hi:[1,1,1]
	v_pk_fma_f32 v[130:131], v[54:55], v[238:239], v[130:131] op_sel_hi:[1,0,1]
	v_pk_fma_f32 v[130:131], v[56:57], v[238:239], v[130:131] op_sel:[0,1,0] op_sel_hi:[1,1,1]
	v_pk_fma_f32 v[130:131], v[58:59], v[240:241], v[130:131] op_sel_hi:[1,0,1]
	v_pk_fma_f32 v[130:131], v[60:61], v[240:241], v[130:131] op_sel:[0,1,0] op_sel_hi:[1,1,1]
	v_pk_fma_f32 v[130:131], v[62:63], v[242:243], v[130:131] op_sel_hi:[1,0,1]
	v_pk_fma_f32 v[130:131], v[64:65], v[242:243], v[130:131] op_sel:[0,1,0] op_sel_hi:[1,1,1]
	v_pk_fma_f32 v[130:131], v[66:67], v[244:245], v[130:131] op_sel_hi:[1,0,1]
	v_pk_fma_f32 v[130:131], v[68:69], v[244:245], v[130:131] op_sel:[0,1,0] op_sel_hi:[1,1,1]
	v_pk_fma_f32 v[130:131], v[70:71], v[246:247], v[130:131] op_sel_hi:[1,0,1]
	v_pk_fma_f32 v[130:131], v[72:73], v[246:247], v[130:131] op_sel:[0,1,0] op_sel_hi:[1,1,1]
	ds_read_b128 v[232:235], v78 offset:448
	ds_read_b128 v[236:239], v78 offset:464
	ds_read_b128 v[240:243], v78 offset:480
	ds_read_b128 v[244:247], v78 offset:496
	v_pk_mul_f32 v[132:133], v[128:129], s[36:37] op_sel_hi:[1,0]
	v_pk_mul_f32 v[134:135], v[130:131], s[36:37] op_sel_hi:[1,0]
	v_exp_f32_e64 v132, -|v132|
	v_exp_f32_e64 v133, -|v133|
	v_exp_f32_e64 v134, -|v134|
	v_exp_f32_e64 v135, -|v135|
	v_pk_add_f32 v[132:133], v[132:133], 1.0 op_sel_hi:[1,0]
	v_pk_add_f32 v[134:135], v[134:135], 1.0 op_sel_hi:[1,0]
	v_log_f32_e32 v136, v132
	v_log_f32_e32 v137, v133
	v_log_f32_e32 v138, v134
	v_log_f32_e32 v139, v135
	v_min_f32_e32 v128, 0, v128
	v_min_f32_e32 v129, 0, v129
	v_min_f32_e32 v130, 0, v130
	v_min_f32_e32 v131, 0, v131
	v_pk_fma_f32 v[100:101], v[136:137], s[36:37], v[128:129] op_sel:[0,1,0] op_sel_hi:[1,1,1]
	v_pk_fma_f32 v[116:117], v[138:139], s[36:37], v[130:131] op_sel:[0,1,0] op_sel_hi:[1,1,1]
	s_waitcnt lgkmcnt(0)
	v_pk_fma_f32 v[128:129], v[10:11], v[216:217], v[74:75] op_sel_hi:[1,0,1]
	v_pk_fma_f32 v[128:129], v[12:13], v[216:217], v[128:129] op_sel:[0,1,0] op_sel_hi:[1,1,1]
	v_pk_fma_f32 v[128:129], v[14:15], v[218:219], v[128:129] op_sel_hi:[1,0,1]
	v_pk_fma_f32 v[128:129], v[16:17], v[218:219], v[128:129] op_sel:[0,1,0] op_sel_hi:[1,1,1]
	v_pk_fma_f32 v[128:129], v[18:19], v[220:221], v[128:129] op_sel_hi:[1,0,1]
	v_pk_fma_f32 v[128:129], v[20:21], v[220:221], v[128:129] op_sel:[0,1,0] op_sel_hi:[1,1,1]
	v_pk_fma_f32 v[128:129], v[22:23], v[222:223], v[128:129] op_sel_hi:[1,0,1]
	v_pk_fma_f32 v[128:129], v[24:25], v[222:223], v[128:129] op_sel:[0,1,0] op_sel_hi:[1,1,1]
	v_pk_fma_f32 v[128:129], v[26:27], v[224:225], v[128:129] op_sel_hi:[1,0,1]
	v_pk_fma_f32 v[128:129], v[28:29], v[224:225], v[128:129] op_sel:[0,1,0] op_sel_hi:[1,1,1]
	v_pk_fma_f32 v[128:129], v[30:31], v[226:227], v[128:129] op_sel_hi:[1,0,1]
	v_pk_fma_f32 v[128:129], v[32:33], v[226:227], v[128:129] op_sel:[0,1,0] op_sel_hi:[1,1,1]
	v_pk_fma_f32 v[128:129], v[34:35], v[228:229], v[128:129] op_sel_hi:[1,0,1]
	v_pk_fma_f32 v[128:129], v[36:37], v[228:229], v[128:129] op_sel:[0,1,0] op_sel_hi:[1,1,1]
	v_pk_fma_f32 v[128:129], v[38:39], v[230:231], v[128:129] op_sel_hi:[1,0,1]
	v_pk_fma_f32 v[128:129], v[40:41], v[230:231], v[128:129] op_sel:[0,1,0] op_sel_hi:[1,1,1]
	ds_read_b128 v[216:219], v78 offset:512
	ds_read_b128 v[220:223], v78 offset:528
	ds_read_b128 v[224:227], v78 offset:544
	ds_read_b128 v[228:231], v78 offset:560
	v_pk_fma_f32 v[130:131], v[42:43], v[232:233], v[76:77] op_sel_hi:[1,0,1]
	v_pk_fma_f32 v[130:131], v[44:45], v[232:233], v[130:131] op_sel:[0,1,0] op_sel_hi:[1,1,1]
	v_pk_fma_f32 v[130:131], v[46:47], v[234:235], v[130:131] op_sel_hi:[1,0,1]
	v_pk_fma_f32 v[130:131], v[48:49], v[234:235], v[130:131] op_sel:[0,1,0] op_sel_hi:[1,1,1]
	v_pk_fma_f32 v[130:131], v[50:51], v[236:237], v[130:131] op_sel_hi:[1,0,1]
	v_pk_fma_f32 v[130:131], v[52:53], v[236:237], v[130:131] op_sel:[0,1,0] op_sel_hi:[1,1,1]
	v_pk_fma_f32 v[130:131], v[54:55], v[238:239], v[130:131] op_sel_hi:[1,0,1]
	v_pk_fma_f32 v[130:131], v[56:57], v[238:239], v[130:131] op_sel:[0,1,0] op_sel_hi:[1,1,1]
	v_pk_fma_f32 v[130:131], v[58:59], v[240:241], v[130:131] op_sel_hi:[1,0,1]
	v_pk_fma_f32 v[130:131], v[60:61], v[240:241], v[130:131] op_sel:[0,1,0] op_sel_hi:[1,1,1]
	v_pk_fma_f32 v[130:131], v[62:63], v[242:243], v[130:131] op_sel_hi:[1,0,1]
	v_pk_fma_f32 v[130:131], v[64:65], v[242:243], v[130:131] op_sel:[0,1,0] op_sel_hi:[1,1,1]
	v_pk_fma_f32 v[130:131], v[66:67], v[244:245], v[130:131] op_sel_hi:[1,0,1]
	v_pk_fma_f32 v[130:131], v[68:69], v[244:245], v[130:131] op_sel:[0,1,0] op_sel_hi:[1,1,1]
	v_pk_fma_f32 v[130:131], v[70:71], v[246:247], v[130:131] op_sel_hi:[1,0,1]
	v_pk_fma_f32 v[130:131], v[72:73], v[246:247], v[130:131] op_sel:[0,1,0] op_sel_hi:[1,1,1]
	ds_read_b128 v[232:235], v78 offset:576
	ds_read_b128 v[236:239], v78 offset:592
	ds_read_b128 v[240:243], v78 offset:608
	ds_read_b128 v[244:247], v78 offset:624
	v_pk_mul_f32 v[132:133], v[128:129], s[36:37] op_sel_hi:[1,0]
	v_pk_mul_f32 v[134:135], v[130:131], s[36:37] op_sel_hi:[1,0]
	v_exp_f32_e64 v132, -|v132|
	v_exp_f32_e64 v133, -|v133|
	v_exp_f32_e64 v134, -|v134|
	v_exp_f32_e64 v135, -|v135|
	v_pk_add_f32 v[132:133], v[132:133], 1.0 op_sel_hi:[1,0]
	v_pk_add_f32 v[134:135], v[134:135], 1.0 op_sel_hi:[1,0]
	v_log_f32_e32 v136, v132
	v_log_f32_e32 v137, v133
	v_log_f32_e32 v138, v134
	v_log_f32_e32 v139, v135
	v_min_f32_e32 v128, 0, v128
	v_min_f32_e32 v129, 0, v129
	v_min_f32_e32 v130, 0, v130
	v_min_f32_e32 v131, 0, v131
	v_pk_fma_f32 v[102:103], v[136:137], s[36:37], v[128:129] op_sel:[0,1,0] op_sel_hi:[1,1,1]
	v_pk_fma_f32 v[118:119], v[138:139], s[36:37], v[130:131] op_sel:[0,1,0] op_sel_hi:[1,1,1]
	s_waitcnt lgkmcnt(0)
	v_pk_fma_f32 v[128:129], v[10:11], v[216:217], v[74:75] op_sel_hi:[1,0,1]
	v_pk_fma_f32 v[128:129], v[12:13], v[216:217], v[128:129] op_sel:[0,1,0] op_sel_hi:[1,1,1]
	v_pk_fma_f32 v[128:129], v[14:15], v[218:219], v[128:129] op_sel_hi:[1,0,1]
	v_pk_fma_f32 v[128:129], v[16:17], v[218:219], v[128:129] op_sel:[0,1,0] op_sel_hi:[1,1,1]
	v_pk_fma_f32 v[128:129], v[18:19], v[220:221], v[128:129] op_sel_hi:[1,0,1]
	v_pk_fma_f32 v[128:129], v[20:21], v[220:221], v[128:129] op_sel:[0,1,0] op_sel_hi:[1,1,1]
	v_pk_fma_f32 v[128:129], v[22:23], v[222:223], v[128:129] op_sel_hi:[1,0,1]
	v_pk_fma_f32 v[128:129], v[24:25], v[222:223], v[128:129] op_sel:[0,1,0] op_sel_hi:[1,1,1]
	v_pk_fma_f32 v[128:129], v[26:27], v[224:225], v[128:129] op_sel_hi:[1,0,1]
	v_pk_fma_f32 v[128:129], v[28:29], v[224:225], v[128:129] op_sel:[0,1,0] op_sel_hi:[1,1,1]
	v_pk_fma_f32 v[128:129], v[30:31], v[226:227], v[128:129] op_sel_hi:[1,0,1]
	v_pk_fma_f32 v[128:129], v[32:33], v[226:227], v[128:129] op_sel:[0,1,0] op_sel_hi:[1,1,1]
	v_pk_fma_f32 v[128:129], v[34:35], v[228:229], v[128:129] op_sel_hi:[1,0,1]
	v_pk_fma_f32 v[128:129], v[36:37], v[228:229], v[128:129] op_sel:[0,1,0] op_sel_hi:[1,1,1]
	v_pk_fma_f32 v[128:129], v[38:39], v[230:231], v[128:129] op_sel_hi:[1,0,1]
	v_pk_fma_f32 v[128:129], v[40:41], v[230:231], v[128:129] op_sel:[0,1,0] op_sel_hi:[1,1,1]
	ds_read_b128 v[216:219], v78 offset:640
	ds_read_b128 v[220:223], v78 offset:656
	ds_read_b128 v[224:227], v78 offset:672
	ds_read_b128 v[228:231], v78 offset:688
	v_pk_fma_f32 v[130:131], v[42:43], v[232:233], v[76:77] op_sel_hi:[1,0,1]
	v_pk_fma_f32 v[130:131], v[44:45], v[232:233], v[130:131] op_sel:[0,1,0] op_sel_hi:[1,1,1]
	v_pk_fma_f32 v[130:131], v[46:47], v[234:235], v[130:131] op_sel_hi:[1,0,1]
	v_pk_fma_f32 v[130:131], v[48:49], v[234:235], v[130:131] op_sel:[0,1,0] op_sel_hi:[1,1,1]
	v_pk_fma_f32 v[130:131], v[50:51], v[236:237], v[130:131] op_sel_hi:[1,0,1]
	v_pk_fma_f32 v[130:131], v[52:53], v[236:237], v[130:131] op_sel:[0,1,0] op_sel_hi:[1,1,1]
	v_pk_fma_f32 v[130:131], v[54:55], v[238:239], v[130:131] op_sel_hi:[1,0,1]
	v_pk_fma_f32 v[130:131], v[56:57], v[238:239], v[130:131] op_sel:[0,1,0] op_sel_hi:[1,1,1]
	v_pk_fma_f32 v[130:131], v[58:59], v[240:241], v[130:131] op_sel_hi:[1,0,1]
	v_pk_fma_f32 v[130:131], v[60:61], v[240:241], v[130:131] op_sel:[0,1,0] op_sel_hi:[1,1,1]
	v_pk_fma_f32 v[130:131], v[62:63], v[242:243], v[130:131] op_sel_hi:[1,0,1]
	v_pk_fma_f32 v[130:131], v[64:65], v[242:243], v[130:131] op_sel:[0,1,0] op_sel_hi:[1,1,1]
	v_pk_fma_f32 v[130:131], v[66:67], v[244:245], v[130:131] op_sel_hi:[1,0,1]
	v_pk_fma_f32 v[130:131], v[68:69], v[244:245], v[130:131] op_sel:[0,1,0] op_sel_hi:[1,1,1]
	v_pk_fma_f32 v[130:131], v[70:71], v[246:247], v[130:131] op_sel_hi:[1,0,1]
	v_pk_fma_f32 v[130:131], v[72:73], v[246:247], v[130:131] op_sel:[0,1,0] op_sel_hi:[1,1,1]
	ds_read_b128 v[232:235], v78 offset:704
	ds_read_b128 v[236:239], v78 offset:720
	ds_read_b128 v[240:243], v78 offset:736
	ds_read_b128 v[244:247], v78 offset:752
	v_pk_mul_f32 v[132:133], v[128:129], s[36:37] op_sel_hi:[1,0]
	v_pk_mul_f32 v[134:135], v[130:131], s[36:37] op_sel_hi:[1,0]
	v_exp_f32_e64 v132, -|v132|
	v_exp_f32_e64 v133, -|v133|
	v_exp_f32_e64 v134, -|v134|
	v_exp_f32_e64 v135, -|v135|
	v_pk_add_f32 v[132:133], v[132:133], 1.0 op_sel_hi:[1,0]
	v_pk_add_f32 v[134:135], v[134:135], 1.0 op_sel_hi:[1,0]
	v_log_f32_e32 v136, v132
	v_log_f32_e32 v137, v133
	v_log_f32_e32 v138, v134
	v_log_f32_e32 v139, v135
	v_min_f32_e32 v128, 0, v128
	v_min_f32_e32 v129, 0, v129
	v_min_f32_e32 v130, 0, v130
	v_min_f32_e32 v131, 0, v131
	v_pk_fma_f32 v[104:105], v[136:137], s[36:37], v[128:129] op_sel:[0,1,0] op_sel_hi:[1,1,1]
	v_pk_fma_f32 v[120:121], v[138:139], s[36:37], v[130:131] op_sel:[0,1,0] op_sel_hi:[1,1,1]
	s_waitcnt lgkmcnt(0)
	v_pk_fma_f32 v[128:129], v[10:11], v[216:217], v[74:75] op_sel_hi:[1,0,1]
	v_pk_fma_f32 v[128:129], v[12:13], v[216:217], v[128:129] op_sel:[0,1,0] op_sel_hi:[1,1,1]
	v_pk_fma_f32 v[128:129], v[14:15], v[218:219], v[128:129] op_sel_hi:[1,0,1]
	v_pk_fma_f32 v[128:129], v[16:17], v[218:219], v[128:129] op_sel:[0,1,0] op_sel_hi:[1,1,1]
	v_pk_fma_f32 v[128:129], v[18:19], v[220:221], v[128:129] op_sel_hi:[1,0,1]
	v_pk_fma_f32 v[128:129], v[20:21], v[220:221], v[128:129] op_sel:[0,1,0] op_sel_hi:[1,1,1]
	v_pk_fma_f32 v[128:129], v[22:23], v[222:223], v[128:129] op_sel_hi:[1,0,1]
	v_pk_fma_f32 v[128:129], v[24:25], v[222:223], v[128:129] op_sel:[0,1,0] op_sel_hi:[1,1,1]
	v_pk_fma_f32 v[128:129], v[26:27], v[224:225], v[128:129] op_sel_hi:[1,0,1]
	v_pk_fma_f32 v[128:129], v[28:29], v[224:225], v[128:129] op_sel:[0,1,0] op_sel_hi:[1,1,1]
	v_pk_fma_f32 v[128:129], v[30:31], v[226:227], v[128:129] op_sel_hi:[1,0,1]
	v_pk_fma_f32 v[128:129], v[32:33], v[226:227], v[128:129] op_sel:[0,1,0] op_sel_hi:[1,1,1]
	v_pk_fma_f32 v[128:129], v[34:35], v[228:229], v[128:129] op_sel_hi:[1,0,1]
	v_pk_fma_f32 v[128:129], v[36:37], v[228:229], v[128:129] op_sel:[0,1,0] op_sel_hi:[1,1,1]
	v_pk_fma_f32 v[128:129], v[38:39], v[230:231], v[128:129] op_sel_hi:[1,0,1]
	v_pk_fma_f32 v[128:129], v[40:41], v[230:231], v[128:129] op_sel:[0,1,0] op_sel_hi:[1,1,1]
	ds_read_b128 v[216:219], v78 offset:768
	ds_read_b128 v[220:223], v78 offset:784
	ds_read_b128 v[224:227], v78 offset:800
	ds_read_b128 v[228:231], v78 offset:816
	v_pk_fma_f32 v[130:131], v[42:43], v[232:233], v[76:77] op_sel_hi:[1,0,1]
	v_pk_fma_f32 v[130:131], v[44:45], v[232:233], v[130:131] op_sel:[0,1,0] op_sel_hi:[1,1,1]
	v_pk_fma_f32 v[130:131], v[46:47], v[234:235], v[130:131] op_sel_hi:[1,0,1]
	v_pk_fma_f32 v[130:131], v[48:49], v[234:235], v[130:131] op_sel:[0,1,0] op_sel_hi:[1,1,1]
	v_pk_fma_f32 v[130:131], v[50:51], v[236:237], v[130:131] op_sel_hi:[1,0,1]
	v_pk_fma_f32 v[130:131], v[52:53], v[236:237], v[130:131] op_sel:[0,1,0] op_sel_hi:[1,1,1]
	v_pk_fma_f32 v[130:131], v[54:55], v[238:239], v[130:131] op_sel_hi:[1,0,1]
	v_pk_fma_f32 v[130:131], v[56:57], v[238:239], v[130:131] op_sel:[0,1,0] op_sel_hi:[1,1,1]
	v_pk_fma_f32 v[130:131], v[58:59], v[240:241], v[130:131] op_sel_hi:[1,0,1]
	v_pk_fma_f32 v[130:131], v[60:61], v[240:241], v[130:131] op_sel:[0,1,0] op_sel_hi:[1,1,1]
	v_pk_fma_f32 v[130:131], v[62:63], v[242:243], v[130:131] op_sel_hi:[1,0,1]
	v_pk_fma_f32 v[130:131], v[64:65], v[242:243], v[130:131] op_sel:[0,1,0] op_sel_hi:[1,1,1]
	v_pk_fma_f32 v[130:131], v[66:67], v[244:245], v[130:131] op_sel_hi:[1,0,1]
	v_pk_fma_f32 v[130:131], v[68:69], v[244:245], v[130:131] op_sel:[0,1,0] op_sel_hi:[1,1,1]
	v_pk_fma_f32 v[130:131], v[70:71], v[246:247], v[130:131] op_sel_hi:[1,0,1]
	v_pk_fma_f32 v[130:131], v[72:73], v[246:247], v[130:131] op_sel:[0,1,0] op_sel_hi:[1,1,1]
	ds_read_b128 v[232:235], v78 offset:832
	ds_read_b128 v[236:239], v78 offset:848
	ds_read_b128 v[240:243], v78 offset:864
	ds_read_b128 v[244:247], v78 offset:880
	v_pk_mul_f32 v[132:133], v[128:129], s[36:37] op_sel_hi:[1,0]
	v_pk_mul_f32 v[134:135], v[130:131], s[36:37] op_sel_hi:[1,0]
	v_exp_f32_e64 v132, -|v132|
	v_exp_f32_e64 v133, -|v133|
	v_exp_f32_e64 v134, -|v134|
	v_exp_f32_e64 v135, -|v135|
	v_pk_add_f32 v[132:133], v[132:133], 1.0 op_sel_hi:[1,0]
	v_pk_add_f32 v[134:135], v[134:135], 1.0 op_sel_hi:[1,0]
	v_log_f32_e32 v136, v132
	v_log_f32_e32 v137, v133
	v_log_f32_e32 v138, v134
	v_log_f32_e32 v139, v135
	v_min_f32_e32 v128, 0, v128
	v_min_f32_e32 v129, 0, v129
	v_min_f32_e32 v130, 0, v130
	v_min_f32_e32 v131, 0, v131
	v_pk_fma_f32 v[106:107], v[136:137], s[36:37], v[128:129] op_sel:[0,1,0] op_sel_hi:[1,1,1]
	v_pk_fma_f32 v[122:123], v[138:139], s[36:37], v[130:131] op_sel:[0,1,0] op_sel_hi:[1,1,1]
	s_waitcnt lgkmcnt(0)
	v_pk_fma_f32 v[128:129], v[10:11], v[216:217], v[74:75] op_sel_hi:[1,0,1]
	v_pk_fma_f32 v[128:129], v[12:13], v[216:217], v[128:129] op_sel:[0,1,0] op_sel_hi:[1,1,1]
	v_pk_fma_f32 v[128:129], v[14:15], v[218:219], v[128:129] op_sel_hi:[1,0,1]
	v_pk_fma_f32 v[128:129], v[16:17], v[218:219], v[128:129] op_sel:[0,1,0] op_sel_hi:[1,1,1]
	v_pk_fma_f32 v[128:129], v[18:19], v[220:221], v[128:129] op_sel_hi:[1,0,1]
	v_pk_fma_f32 v[128:129], v[20:21], v[220:221], v[128:129] op_sel:[0,1,0] op_sel_hi:[1,1,1]
	v_pk_fma_f32 v[128:129], v[22:23], v[222:223], v[128:129] op_sel_hi:[1,0,1]
	v_pk_fma_f32 v[128:129], v[24:25], v[222:223], v[128:129] op_sel:[0,1,0] op_sel_hi:[1,1,1]
	v_pk_fma_f32 v[128:129], v[26:27], v[224:225], v[128:129] op_sel_hi:[1,0,1]
	v_pk_fma_f32 v[128:129], v[28:29], v[224:225], v[128:129] op_sel:[0,1,0] op_sel_hi:[1,1,1]
	v_pk_fma_f32 v[128:129], v[30:31], v[226:227], v[128:129] op_sel_hi:[1,0,1]
	v_pk_fma_f32 v[128:129], v[32:33], v[226:227], v[128:129] op_sel:[0,1,0] op_sel_hi:[1,1,1]
	v_pk_fma_f32 v[128:129], v[34:35], v[228:229], v[128:129] op_sel_hi:[1,0,1]
	v_pk_fma_f32 v[128:129], v[36:37], v[228:229], v[128:129] op_sel:[0,1,0] op_sel_hi:[1,1,1]
	v_pk_fma_f32 v[128:129], v[38:39], v[230:231], v[128:129] op_sel_hi:[1,0,1]
	v_pk_fma_f32 v[128:129], v[40:41], v[230:231], v[128:129] op_sel:[0,1,0] op_sel_hi:[1,1,1]
	ds_read_b128 v[216:219], v78 offset:896
	ds_read_b128 v[220:223], v78 offset:912
	ds_read_b128 v[224:227], v78 offset:928
	ds_read_b128 v[228:231], v78 offset:944
	v_pk_fma_f32 v[130:131], v[42:43], v[232:233], v[76:77] op_sel_hi:[1,0,1]
	v_pk_fma_f32 v[130:131], v[44:45], v[232:233], v[130:131] op_sel:[0,1,0] op_sel_hi:[1,1,1]
	v_pk_fma_f32 v[130:131], v[46:47], v[234:235], v[130:131] op_sel_hi:[1,0,1]
	v_pk_fma_f32 v[130:131], v[48:49], v[234:235], v[130:131] op_sel:[0,1,0] op_sel_hi:[1,1,1]
	v_pk_fma_f32 v[130:131], v[50:51], v[236:237], v[130:131] op_sel_hi:[1,0,1]
	v_pk_fma_f32 v[130:131], v[52:53], v[236:237], v[130:131] op_sel:[0,1,0] op_sel_hi:[1,1,1]
	v_pk_fma_f32 v[130:131], v[54:55], v[238:239], v[130:131] op_sel_hi:[1,0,1]
	v_pk_fma_f32 v[130:131], v[56:57], v[238:239], v[130:131] op_sel:[0,1,0] op_sel_hi:[1,1,1]
	v_pk_fma_f32 v[130:131], v[58:59], v[240:241], v[130:131] op_sel_hi:[1,0,1]
	v_pk_fma_f32 v[130:131], v[60:61], v[240:241], v[130:131] op_sel:[0,1,0] op_sel_hi:[1,1,1]
	v_pk_fma_f32 v[130:131], v[62:63], v[242:243], v[130:131] op_sel_hi:[1,0,1]
	v_pk_fma_f32 v[130:131], v[64:65], v[242:243], v[130:131] op_sel:[0,1,0] op_sel_hi:[1,1,1]
	v_pk_fma_f32 v[130:131], v[66:67], v[244:245], v[130:131] op_sel_hi:[1,0,1]
	v_pk_fma_f32 v[130:131], v[68:69], v[244:245], v[130:131] op_sel:[0,1,0] op_sel_hi:[1,1,1]
	v_pk_fma_f32 v[130:131], v[70:71], v[246:247], v[130:131] op_sel_hi:[1,0,1]
	v_pk_fma_f32 v[130:131], v[72:73], v[246:247], v[130:131] op_sel:[0,1,0] op_sel_hi:[1,1,1]
	ds_read_b128 v[232:235], v78 offset:960
	ds_read_b128 v[236:239], v78 offset:976
	ds_read_b128 v[240:243], v78 offset:992
	ds_read_b128 v[244:247], v78 offset:1008
	v_pk_mul_f32 v[132:133], v[128:129], s[36:37] op_sel_hi:[1,0]
	v_pk_mul_f32 v[134:135], v[130:131], s[36:37] op_sel_hi:[1,0]
	v_exp_f32_e64 v132, -|v132|
	v_exp_f32_e64 v133, -|v133|
	v_exp_f32_e64 v134, -|v134|
	v_exp_f32_e64 v135, -|v135|
	v_pk_add_f32 v[132:133], v[132:133], 1.0 op_sel_hi:[1,0]
	v_pk_add_f32 v[134:135], v[134:135], 1.0 op_sel_hi:[1,0]
	v_log_f32_e32 v136, v132
	v_log_f32_e32 v137, v133
	v_log_f32_e32 v138, v134
	v_log_f32_e32 v139, v135
	v_min_f32_e32 v128, 0, v128
	v_min_f32_e32 v129, 0, v129
	v_min_f32_e32 v130, 0, v130
	v_min_f32_e32 v131, 0, v131
	v_pk_fma_f32 v[108:109], v[136:137], s[36:37], v[128:129] op_sel:[0,1,0] op_sel_hi:[1,1,1]
	v_pk_fma_f32 v[124:125], v[138:139], s[36:37], v[130:131] op_sel:[0,1,0] op_sel_hi:[1,1,1]
	s_waitcnt lgkmcnt(0)
	v_pk_fma_f32 v[128:129], v[10:11], v[216:217], v[74:75] op_sel_hi:[1,0,1]
	v_pk_fma_f32 v[128:129], v[12:13], v[216:217], v[128:129] op_sel:[0,1,0] op_sel_hi:[1,1,1]
	v_pk_fma_f32 v[128:129], v[14:15], v[218:219], v[128:129] op_sel_hi:[1,0,1]
	v_pk_fma_f32 v[128:129], v[16:17], v[218:219], v[128:129] op_sel:[0,1,0] op_sel_hi:[1,1,1]
	v_pk_fma_f32 v[128:129], v[18:19], v[220:221], v[128:129] op_sel_hi:[1,0,1]
	v_pk_fma_f32 v[128:129], v[20:21], v[220:221], v[128:129] op_sel:[0,1,0] op_sel_hi:[1,1,1]
	v_pk_fma_f32 v[128:129], v[22:23], v[222:223], v[128:129] op_sel_hi:[1,0,1]
	v_pk_fma_f32 v[128:129], v[24:25], v[222:223], v[128:129] op_sel:[0,1,0] op_sel_hi:[1,1,1]
	v_pk_fma_f32 v[128:129], v[26:27], v[224:225], v[128:129] op_sel_hi:[1,0,1]
	v_pk_fma_f32 v[128:129], v[28:29], v[224:225], v[128:129] op_sel:[0,1,0] op_sel_hi:[1,1,1]
	v_pk_fma_f32 v[128:129], v[30:31], v[226:227], v[128:129] op_sel_hi:[1,0,1]
	v_pk_fma_f32 v[128:129], v[32:33], v[226:227], v[128:129] op_sel:[0,1,0] op_sel_hi:[1,1,1]
	v_pk_fma_f32 v[128:129], v[34:35], v[228:229], v[128:129] op_sel_hi:[1,0,1]
	v_pk_fma_f32 v[128:129], v[36:37], v[228:229], v[128:129] op_sel:[0,1,0] op_sel_hi:[1,1,1]
	v_pk_fma_f32 v[128:129], v[38:39], v[230:231], v[128:129] op_sel_hi:[1,0,1]
	v_pk_fma_f32 v[128:129], v[40:41], v[230:231], v[128:129] op_sel:[0,1,0] op_sel_hi:[1,1,1]
	v_pk_fma_f32 v[130:131], v[42:43], v[232:233], v[76:77] op_sel_hi:[1,0,1]
	v_pk_fma_f32 v[130:131], v[44:45], v[232:233], v[130:131] op_sel:[0,1,0] op_sel_hi:[1,1,1]
	v_pk_fma_f32 v[130:131], v[46:47], v[234:235], v[130:131] op_sel_hi:[1,0,1]
	v_pk_fma_f32 v[130:131], v[48:49], v[234:235], v[130:131] op_sel:[0,1,0] op_sel_hi:[1,1,1]
	v_pk_fma_f32 v[130:131], v[50:51], v[236:237], v[130:131] op_sel_hi:[1,0,1]
	v_pk_fma_f32 v[130:131], v[52:53], v[236:237], v[130:131] op_sel:[0,1,0] op_sel_hi:[1,1,1]
	v_pk_fma_f32 v[130:131], v[54:55], v[238:239], v[130:131] op_sel_hi:[1,0,1]
	v_pk_fma_f32 v[130:131], v[56:57], v[238:239], v[130:131] op_sel:[0,1,0] op_sel_hi:[1,1,1]
	v_pk_fma_f32 v[130:131], v[58:59], v[240:241], v[130:131] op_sel_hi:[1,0,1]
	v_pk_fma_f32 v[130:131], v[60:61], v[240:241], v[130:131] op_sel:[0,1,0] op_sel_hi:[1,1,1]
	v_pk_fma_f32 v[130:131], v[62:63], v[242:243], v[130:131] op_sel_hi:[1,0,1]
	v_pk_fma_f32 v[130:131], v[64:65], v[242:243], v[130:131] op_sel:[0,1,0] op_sel_hi:[1,1,1]
	v_pk_fma_f32 v[130:131], v[66:67], v[244:245], v[130:131] op_sel_hi:[1,0,1]
	v_pk_fma_f32 v[130:131], v[68:69], v[244:245], v[130:131] op_sel:[0,1,0] op_sel_hi:[1,1,1]
	v_pk_fma_f32 v[130:131], v[70:71], v[246:247], v[130:131] op_sel_hi:[1,0,1]
	v_pk_fma_f32 v[130:131], v[72:73], v[246:247], v[130:131] op_sel:[0,1,0] op_sel_hi:[1,1,1]
	v_pk_mul_f32 v[132:133], v[128:129], s[36:37] op_sel_hi:[1,0]
	v_pk_mul_f32 v[134:135], v[130:131], s[36:37] op_sel_hi:[1,0]
	v_exp_f32_e64 v132, -|v132|
	v_exp_f32_e64 v133, -|v133|
	v_exp_f32_e64 v134, -|v134|
	v_exp_f32_e64 v135, -|v135|
	v_pk_add_f32 v[132:133], v[132:133], 1.0 op_sel_hi:[1,0]
	v_pk_add_f32 v[134:135], v[134:135], 1.0 op_sel_hi:[1,0]
	v_log_f32_e32 v136, v132
	v_log_f32_e32 v137, v133
	v_log_f32_e32 v138, v134
	v_log_f32_e32 v139, v135
	v_min_f32_e32 v128, 0, v128
	v_min_f32_e32 v129, 0, v129
	v_min_f32_e32 v130, 0, v130
	v_min_f32_e32 v131, 0, v131
	v_pk_fma_f32 v[110:111], v[136:137], s[36:37], v[128:129] op_sel:[0,1,0] op_sel_hi:[1,1,1]
	v_pk_fma_f32 v[126:127], v[138:139], s[36:37], v[130:131] op_sel:[0,1,0] op_sel_hi:[1,1,1]
	v_readlane_b32 s69, v251, 49
	s_nop 3
	s_add_i32 s56, s56, 64
	s_movk_i32 s51, 0x480
	s_cmpk_lt_i32 s56, 0x120
	s_cbranch_scc0 .Lp7_jdone
	s_mul_hi_u32 s57, s56, 0x71c71c8
	s_mul_i32 s51, s57, 108
	s_add_i32 s51, s51, s56
	s_and_b32 s57, s58, 3
	s_mul_i32 s57, s57, 36
	s_add_i32 s51, s51, s57

.Lp7_dec_done:
	v_pk_mul_f32 v[132:133], v[132:133], s[32:33] op_sel:[0,1] op_sel_hi:[1,1]
	v_pk_mul_f32 v[134:135], v[134:135], s[32:33] op_sel:[0,1] op_sel_hi:[1,1]
	s_mov_b64 s[52:53], s[42:43]
	s_mov_b64 s[54:55], s[46:47]
	v_pk_fma_f32 v[96:97], v[96:97], s[32:33], v[132:133] op_sel:[0,1,0] op_sel_hi:[1,1,1]
	v_pk_fma_f32 v[112:113], v[112:113], s[32:33], v[134:135] op_sel:[0,1,0] op_sel_hi:[1,1,1]
	v_exp_f32_e32 v136, v96
	v_exp_f32_e32 v137, v97
	v_exp_f32_e32 v138, v112
	v_exp_f32_e32 v139, v113
	v_lshlrev_b32_e32 v140, 16, v80
	v_and_b32_e32 v141, 0xffff0000, v80
	v_pk_mul_f32 v[136:137], v[140:141], v[136:137]
	v_pk_mul_f32 v[138:139], v[140:141], v[138:139]
	v_cvt_pk_bf16_f32 v142, v136, v137
	v_cvt_pk_bf16_f32 v143, v138, v139
	global_store_dword v2, v142, s[52:53] offset:1024
	global_store_dword v2, v143, s[54:55]
	s_add_u32 s52, s52, 0x1800
	s_addc_u32 s53, s53, 0
	s_add_u32 s54, s54, 0x400
	s_addc_u32 s55, s55, 0
	v_pk_fma_f32 v[98:99], v[98:99], s[32:33], v[132:133] op_sel:[0,1,0] op_sel_hi:[1,1,1]
	v_pk_fma_f32 v[114:115], v[114:115], s[32:33], v[134:135] op_sel:[0,1,0] op_sel_hi:[1,1,1]
	v_exp_f32_e32 v136, v98
	v_exp_f32_e32 v137, v99
	v_exp_f32_e32 v138, v114
	v_exp_f32_e32 v139, v115
	v_lshlrev_b32_e32 v140, 16, v81
	v_and_b32_e32 v141, 0xffff0000, v81
	v_pk_mul_f32 v[136:137], v[140:141], v[136:137]
	v_pk_mul_f32 v[138:139], v[140:141], v[138:139]
	v_cvt_pk_bf16_f32 v142, v136, v137
	v_cvt_pk_bf16_f32 v143, v138, v139
	global_store_dword v2, v142, s[52:53] offset:1024
	global_store_dword v2, v143, s[54:55]
	s_add_u32 s52, s52, 0x1800
	s_addc_u32 s53, s53, 0
	s_add_u32 s54, s54, 0x400
	s_addc_u32 s55, s55, 0
	v_pk_fma_f32 v[100:101], v[100:101], s[32:33], v[132:133] op_sel:[0,1,0] op_sel_hi:[1,1,1]
	v_pk_fma_f32 v[116:117], v[116:117], s[32:33], v[134:135] op_sel:[0,1,0] op_sel_hi:[1,1,1]
	v_exp_f32_e32 v136, v100
	v_exp_f32_e32 v137, v101
	v_exp_f32_e32 v138, v116
	v_exp_f32_e32 v139, v117
	v_lshlrev_b32_e32 v140, 16, v82
	v_and_b32_e32 v141, 0xffff0000, v82
	v_pk_mul_f32 v[136:137], v[140:141], v[136:137]
	v_pk_mul_f32 v[138:139], v[140:141], v[138:139]
	v_cvt_pk_bf16_f32 v142, v136, v137
	v_cvt_pk_bf16_f32 v143, v138, v139
	global_store_dword v2, v142, s[52:53] offset:1024
	global_store_dword v2, v143, s[54:55]
	s_add_u32 s52, s52, 0x1800
	s_addc_u32 s53, s53, 0
	s_add_u32 s54, s54, 0x400
	s_addc_u32 s55, s55, 0
	v_pk_fma_f32 v[102:103], v[102:103], s[32:33], v[132:133] op_sel:[0,1,0] op_sel_hi:[1,1,1]
	v_pk_fma_f32 v[118:119], v[118:119], s[32:33], v[134:135] op_sel:[0,1,0] op_sel_hi:[1,1,1]
	v_exp_f32_e32 v136, v102
	v_exp_f32_e32 v137, v103
	v_exp_f32_e32 v138, v118
	v_exp_f32_e32 v139, v119
	v_lshlrev_b32_e32 v140, 16, v83
	v_and_b32_e32 v141, 0xffff0000, v83
	v_pk_mul_f32 v[136:137], v[140:141], v[136:137]
	v_pk_mul_f32 v[138:139], v[140:141], v[138:139]
	v_cvt_pk_bf16_f32 v142, v136, v137
	v_cvt_pk_bf16_f32 v143, v138, v139
	global_store_dword v2, v142, s[52:53] offset:1024
	global_store_dword v2, v143, s[54:55]
	s_add_u32 s52, s52, 0x1800
	s_addc_u32 s53, s53, 0
	s_add_u32 s54, s54, 0x400
	s_addc_u32 s55, s55, 0
	v_pk_fma_f32 v[104:105], v[104:105], s[32:33], v[132:133] op_sel:[0,1,0] op_sel_hi:[1,1,1]
	v_pk_fma_f32 v[120:121], v[120:121], s[32:33], v[134:135] op_sel:[0,1,0] op_sel_hi:[1,1,1]
	v_exp_f32_e32 v136, v104
	v_exp_f32_e32 v137, v105
	v_exp_f32_e32 v138, v120
	v_exp_f32_e32 v139, v121
	v_lshlrev_b32_e32 v140, 16, v84
	v_and_b32_e32 v141, 0xffff0000, v84
	v_pk_mul_f32 v[136:137], v[140:141], v[136:137]
	v_pk_mul_f32 v[138:139], v[140:141], v[138:139]
	v_cvt_pk_bf16_f32 v142, v136, v137
	v_cvt_pk_bf16_f32 v143, v138, v139
	global_store_dword v2, v142, s[52:53] offset:1024
	global_store_dword v2, v143, s[54:55]
	s_add_u32 s52, s52, 0x1800
	s_addc_u32 s53, s53, 0
	s_add_u32 s54, s54, 0x400
	s_addc_u32 s55, s55, 0
	v_pk_fma_f32 v[106:107], v[106:107], s[32:33], v[132:133] op_sel:[0,1,0] op_sel_hi:[1,1,1]
	v_pk_fma_f32 v[122:123], v[122:123], s[32:33], v[134:135] op_sel:[0,1,0] op_sel_hi:[1,1,1]
	v_exp_f32_e32 v136, v106
	v_exp_f32_e32 v137, v107
	v_exp_f32_e32 v138, v122
	v_exp_f32_e32 v139, v123
	v_lshlrev_b32_e32 v140, 16, v85
	v_and_b32_e32 v141, 0xffff0000, v85
	v_pk_mul_f32 v[136:137], v[140:141], v[136:137]
	v_pk_mul_f32 v[138:139], v[140:141], v[138:139]
	v_cvt_pk_bf16_f32 v142, v136, v137
	v_cvt_pk_bf16_f32 v143, v138, v139
	global_store_dword v2, v142, s[52:53] offset:1024
	global_store_dword v2, v143, s[54:55]
	s_add_u32 s52, s52, 0x1800
	s_addc_u32 s53, s53, 0
	s_add_u32 s54, s54, 0x400
	s_addc_u32 s55, s55, 0
	v_pk_fma_f32 v[108:109], v[108:109], s[32:33], v[132:133] op_sel:[0,1,0] op_sel_hi:[1,1,1]
	v_pk_fma_f32 v[124:125], v[124:125], s[32:33], v[134:135] op_sel:[0,1,0] op_sel_hi:[1,1,1]
	v_exp_f32_e32 v136, v108
	v_exp_f32_e32 v137, v109
	v_exp_f32_e32 v138, v124
	v_exp_f32_e32 v139, v125
	v_lshlrev_b32_e32 v140, 16, v86
	v_and_b32_e32 v141, 0xffff0000, v86
	v_pk_mul_f32 v[136:137], v[140:141], v[136:137]
	v_pk_mul_f32 v[138:139], v[140:141], v[138:139]
	v_cvt_pk_bf16_f32 v142, v136, v137
	v_cvt_pk_bf16_f32 v143, v138, v139
	global_store_dword v2, v142, s[52:53] offset:1024
	global_store_dword v2, v143, s[54:55]
	s_add_u32 s52, s52, 0x1800
	s_addc_u32 s53, s53, 0
	s_add_u32 s54, s54, 0x400
	s_addc_u32 s55, s55, 0
	v_pk_fma_f32 v[110:111], v[110:111], s[32:33], v[132:133] op_sel:[0,1,0] op_sel_hi:[1,1,1]
	v_pk_fma_f32 v[126:127], v[126:127], s[32:33], v[134:135] op_sel:[0,1,0] op_sel_hi:[1,1,1]
	v_exp_f32_e32 v136, v110
	v_exp_f32_e32 v137, v111
	v_exp_f32_e32 v138, v126
	v_exp_f32_e32 v139, v127
	v_lshlrev_b32_e32 v140, 16, v87
	v_and_b32_e32 v141, 0xffff0000, v87
	v_pk_mul_f32 v[136:137], v[140:141], v[136:137]
	v_pk_mul_f32 v[138:139], v[140:141], v[138:139]
	v_cvt_pk_bf16_f32 v142, v136, v137
	v_cvt_pk_bf16_f32 v143, v138, v139
	global_store_dword v2, v142, s[52:53] offset:1024
	global_store_dword v2, v143, s[54:55]
	s_cmp_lt_u32 s39, 4
	s_cbranch_scc1 .Lp7_noq_store
	s_mov_b64 s[52:53], s[42:43]
	s_mov_b64 s[54:55], s[44:45]
	v_exp_f32_e64 v136, -v96
	v_exp_f32_e64 v137, -v97
	v_exp_f32_e64 v138, -v112
	v_exp_f32_e64 v139, -v113
	v_lshlrev_b32_e32 v140, 16, v88
	v_and_b32_e32 v141, 0xffff0000, v88
	v_pk_mul_f32 v[136:137], v[140:141], v[136:137]
	v_pk_mul_f32 v[138:139], v[140:141], v[138:139]
	v_cvt_pk_bf16_f32 v142, v136, v137
	v_cvt_pk_bf16_f32 v143, v138, v139
	global_store_dword v2, v142, s[52:53]
	global_store_dword v2, v143, s[54:55]
	s_add_u32 s52, s52, 0x1800
	s_addc_u32 s53, s53, 0
	s_add_u32 s54, s54, 0x400
	s_addc_u32 s55, s55, 0
	v_exp_f32_e64 v136, -v98
	v_exp_f32_e64 v137, -v99
	v_exp_f32_e64 v138, -v114
	v_exp_f32_e64 v139, -v115
	v_lshlrev_b32_e32 v140, 16, v89
	v_and_b32_e32 v141, 0xffff0000, v89
	v_pk_mul_f32 v[136:137], v[140:141], v[136:137]
	v_pk_mul_f32 v[138:139], v[140:141], v[138:139]
	v_cvt_pk_bf16_f32 v142, v136, v137
	v_cvt_pk_bf16_f32 v143, v138, v139
	global_store_dword v2, v142, s[52:53]
	global_store_dword v2, v143, s[54:55]
	s_add_u32 s52, s52, 0x1800
	s_addc_u32 s53, s53, 0
	s_add_u32 s54, s54, 0x400
	s_addc_u32 s55, s55, 0
	v_exp_f32_e64 v136, -v100
	v_exp_f32_e64 v137, -v101
	v_exp_f32_e64 v138, -v116
	v_exp_f32_e64 v139, -v117
	v_lshlrev_b32_e32 v140, 16, v90
	v_and_b32_e32 v141, 0xffff0000, v90
	v_pk_mul_f32 v[136:137], v[140:141], v[136:137]
	v_pk_mul_f32 v[138:139], v[140:141], v[138:139]
	v_cvt_pk_bf16_f32 v142, v136, v137
	v_cvt_pk_bf16_f32 v143, v138, v139
	global_store_dword v2, v142, s[52:53]
	global_store_dword v2, v143, s[54:55]
	s_add_u32 s52, s52, 0x1800
	s_addc_u32 s53, s53, 0
	s_add_u32 s54, s54, 0x400
	s_addc_u32 s55, s55, 0
	v_exp_f32_e64 v136, -v102
	v_exp_f32_e64 v137, -v103
	v_exp_f32_e64 v138, -v118
	v_exp_f32_e64 v139, -v119
	v_lshlrev_b32_e32 v140, 16, v91
	v_and_b32_e32 v141, 0xffff0000, v91
	v_pk_mul_f32 v[136:137], v[140:141], v[136:137]
	v_pk_mul_f32 v[138:139], v[140:141], v[138:139]
	v_cvt_pk_bf16_f32 v142, v136, v137
	v_cvt_pk_bf16_f32 v143, v138, v139
	global_store_dword v2, v142, s[52:53]
	global_store_dword v2, v143, s[54:55]
	s_add_u32 s52, s52, 0x1800
	s_addc_u32 s53, s53, 0
	s_add_u32 s54, s54, 0x400
	s_addc_u32 s55, s55, 0
	v_exp_f32_e64 v136, -v104
	v_exp_f32_e64 v137, -v105
	v_exp_f32_e64 v138, -v120
	v_exp_f32_e64 v139, -v121
	v_lshlrev_b32_e32 v140, 16, v92
	v_and_b32_e32 v141, 0xffff0000, v92
	v_pk_mul_f32 v[136:137], v[140:141], v[136:137]
	v_pk_mul_f32 v[138:139], v[140:141], v[138:139]
	v_cvt_pk_bf16_f32 v142, v136, v137
	v_cvt_pk_bf16_f32 v143, v138, v139
	global_store_dword v2, v142, s[52:53]
	global_store_dword v2, v143, s[54:55]
	s_add_u32 s52, s52, 0x1800
	s_addc_u32 s53, s53, 0
	s_add_u32 s54, s54, 0x400
	s_addc_u32 s55, s55, 0
	v_exp_f32_e64 v136, -v106
	v_exp_f32_e64 v137, -v107
	v_exp_f32_e64 v138, -v122
	v_exp_f32_e64 v139, -v123
	v_lshlrev_b32_e32 v140, 16, v93
	v_and_b32_e32 v141, 0xffff0000, v93
	v_pk_mul_f32 v[136:137], v[140:141], v[136:137]
	v_pk_mul_f32 v[138:139], v[140:141], v[138:139]
	v_cvt_pk_bf16_f32 v142, v136, v137
	v_cvt_pk_bf16_f32 v143, v138, v139
	global_store_dword v2, v142, s[52:53]
	global_store_dword v2, v143, s[54:55]
	s_add_u32 s52, s52, 0x1800
	s_addc_u32 s53, s53, 0
	s_add_u32 s54, s54, 0x400
	s_addc_u32 s55, s55, 0
	v_exp_f32_e64 v136, -v108
	v_exp_f32_e64 v137, -v109
	v_exp_f32_e64 v138, -v124
	v_exp_f32_e64 v139, -v125
	v_lshlrev_b32_e32 v140, 16, v94
	v_and_b32_e32 v141, 0xffff0000, v94
	v_pk_mul_f32 v[136:137], v[140:141], v[136:137]
	v_pk_mul_f32 v[138:139], v[140:141], v[138:139]
	v_cvt_pk_bf16_f32 v142, v136, v137
	v_cvt_pk_bf16_f32 v143, v138, v139
	global_store_dword v2, v142, s[52:53]
	global_store_dword v2, v143, s[54:55]
	s_add_u32 s52, s52, 0x1800
	s_addc_u32 s53, s53, 0
	s_add_u32 s54, s54, 0x400
	s_addc_u32 s55, s55, 0
	v_exp_f32_e64 v136, -v110
	v_exp_f32_e64 v137, -v111
	v_exp_f32_e64 v138, -v126
	v_exp_f32_e64 v139, -v127
	v_lshlrev_b32_e32 v140, 16, v95
	v_and_b32_e32 v141, 0xffff0000, v95
	v_pk_mul_f32 v[136:137], v[140:141], v[136:137]
	v_pk_mul_f32 v[138:139], v[140:141], v[138:139]
	v_cvt_pk_bf16_f32 v142, v136, v137
	v_cvt_pk_bf16_f32 v143, v138, v139
	global_store_dword v2, v142, s[52:53]
	global_store_dword v2, v143, s[54:55]
